# adds: MLA step loop back-edge rotated - vprev/l copy and group dispatch test moved in front of the step barrier; looping waves branch straight to their group's first block
# speedup vs baseline: 1.0053x; 1.0020x over previous
.Lrot_pvb:
	s_setprio 1
	v_lshl_add_u32 v210, s37, 14, v218
	s_waitcnt lgkmcnt(0)
	s_nop 0
	v_mfma_f32_32x32x16_bf16 v[32:47], v[76:79], v[154:157], v[32:47]
	ds_read_b64_tr_b16 v[80:81], v210 offset:0x200
	ds_read_b64_tr_b16 v[82:83], v210 offset:0xa00
	v_mfma_f32_32x32x16_bf16 v[32:47], v[72:75], v[158:161], v[32:47]
	ds_read_b64_tr_b16 v[84:85], v210 offset:0x1200
	ds_read_b64_tr_b16 v[86:87], v210 offset:0x1a00
	v_mfma_f32_32x32x16_bf16 v[32:47], v[68:71], v[162:165], v[32:47]
	ds_read_b64_tr_b16 v[88:89], v210 offset:0x2200
	ds_read_b64_tr_b16 v[90:91], v210 offset:0x2a00
	v_mfma_f32_32x32x16_bf16 v[32:47], v[64:67], v[206:209], v[32:47]
	ds_read_b64_tr_b16 v[92:93], v210 offset:0x3200
	ds_read_b64_tr_b16 v[94:95], v210 offset:0x3a00
	s_waitcnt lgkmcnt(0)
	v_mfma_f32_32x32x16_bf16 v[48:63], v[76:79], v[80:83], v[48:63]
	ds_read_b64_tr_b16 v[80:81], v210 offset:0x400
	ds_read_b64_tr_b16 v[82:83], v210 offset:0xc00
	v_mfma_f32_32x32x16_bf16 v[48:63], v[72:75], v[84:87], v[48:63]
	ds_read_b64_tr_b16 v[84:85], v210 offset:0x1400
	ds_read_b64_tr_b16 v[86:87], v210 offset:0x1c00
	v_mfma_f32_32x32x16_bf16 v[48:63], v[68:71], v[88:91], v[48:63]
	ds_read_b64_tr_b16 v[88:89], v210 offset:0x2400
	ds_read_b64_tr_b16 v[90:91], v210 offset:0x2c00
	v_mfma_f32_32x32x16_bf16 v[48:63], v[64:67], v[92:95], v[48:63]
	ds_read_b64_tr_b16 v[92:93], v210 offset:0x3400
	ds_read_b64_tr_b16 v[94:95], v210 offset:0x3c00
	s_waitcnt lgkmcnt(0)
	v_mfma_f32_32x32x16_bf16 v[16:31], v[76:79], v[80:83], v[16:31]
	ds_read_b64_tr_b16 v[80:81], v210 offset:0x600
	ds_read_b64_tr_b16 v[82:83], v210 offset:0xe00
	v_mfma_f32_32x32x16_bf16 v[16:31], v[72:75], v[84:87], v[16:31]
	ds_read_b64_tr_b16 v[84:85], v210 offset:0x1600
	ds_read_b64_tr_b16 v[86:87], v210 offset:0x1e00
	v_mfma_f32_32x32x16_bf16 v[16:31], v[68:71], v[88:91], v[16:31]
	ds_read_b64_tr_b16 v[88:89], v210 offset:0x2600
	ds_read_b64_tr_b16 v[90:91], v210 offset:0x2e00
	v_mfma_f32_32x32x16_bf16 v[16:31], v[64:67], v[92:95], v[16:31]
	ds_read_b64_tr_b16 v[92:93], v210 offset:0x3600
	ds_read_b64_tr_b16 v[94:95], v210 offset:0x3e00
	s_waitcnt lgkmcnt(0)
	v_mfma_f32_32x32x16_bf16 v[0:15], v[76:79], v[80:83], v[0:15]
	v_mfma_f32_32x32x16_bf16 v[0:15], v[72:75], v[84:87], v[0:15]
	v_mfma_f32_32x32x16_bf16 v[0:15], v[68:71], v[88:91], v[0:15]
	v_mfma_f32_32x32x16_bf16 v[0:15], v[64:67], v[92:95], v[0:15]
	s_setprio 0

.Lpv3_bskip:
.LBB0_159:
	s_add_i32 s57, s57, 1
	v_add_f32_e32 v80, v80, v81
	s_ashr_i32 m0, s100, 7
	s_sub_i32 s69, s69, m0
	s_add_i32 s8, s8, m0
	s_add_i32 s37, s63, s57
	s_mul_i32 s42, s100, 24
	s_mov_b32 s43, s101
	v_fmac_f32_e32 v80, v233, v234
	s_and_b64 vcc, exec, s[80:81]
	s_cmp_eq_u32 s37, 2
	s_mov_b32 s37, s70
	v_mov_b32_e32 v233, v80
	s_barrier
	s_cbranch_scc1 .LBB0_161
	s_mov_b32 s70, s36
	s_cbranch_vccz .LBB0_148
	s_branch .Lrot_pvb
